# LayerNorm phases: wave reductions via permlane32/16 swap and DPP row rotations instead of six ds_bpermute LDS round trips each (bit-identical sums)
# baseline (speedup 1.0000x reference)
; DEV void phase_ln(const Params& p, int l) {
;     ...
;     if (l != 0) {
;       float s = 0;
; #pragma unroll
;       for (int i = 0; i < 16; ++i) s += v[i];
;       float mean = wave_sum(s, lane) * (1.f / 1024.f);
;       float q2 = 0;
; #pragma unroll
;       for (int i = 0; i < 16; ++i) { v[i] -= mean; q2 += v[i] * v[i]; }
;       float rstd = rsqrtf(wave_sum(q2, lane) * (1.f / 1024.f) + LN_EPS);
;       const float* g = p.ln_g + (l - 1) * 1024; const float* bb = p.ln_b + (l - 1) * 1024;
; #pragma unroll
;       for (int q = 0; q < 4; ++q) { float4 gg = *reinterpret_cast<const float4*>(g + q * 256 + lane * 4); float4 b4 = *reinterpret_cast<const float4*>(bb + q * 256 + lane * 4);
;         v[q * 4] = v[q * 4] * rstd * gg.x + b4.x; v[q * 4 + 1] = v[q * 4 + 1] * rstd * gg.y + b4.y; v[q * 4 + 2] = v[q * 4 + 2] * rstd * gg.z + b4.z; v[q * 4 + 3] = v[q * 4 + 3] * rstd * gg.w + b4.w; }
.LBB0_165:
	s_or_b64 exec, exec, s[16:17]
	s_and_b64 s[0:1], exec, s[0:1]
	s_or_b64 s[12:13], s[0:1], s[12:13]
	s_andn2_b64 vcc, exec, s[8:9]
	s_cbranch_vccnz .LBB0_167
	v_add_f32_e32 v33, 0, v12
	v_add_f32_e32 v33, v13, v33
	v_add_f32_e32 v33, v14, v33
	v_add_f32_e32 v33, v15, v33
	v_add_f32_e32 v33, v8, v33
	v_add_f32_e32 v33, v9, v33
	v_add_f32_e32 v33, v10, v33
	v_add_f32_e32 v33, v11, v33
	v_add_f32_e32 v33, v4, v33
	v_add_f32_e32 v33, v5, v33
	v_add_f32_e32 v33, v6, v33
	v_add_f32_e32 v33, v7, v33
	v_add_f32_e32 v33, v0, v33
	v_add_f32_e32 v33, v1, v33
	v_add_f32_e32 v33, v2, v33
	v_add_f32_e32 v33, v3, v33
	v_mov_b32_e32 v34, v33
	s_nop 1
	v_permlane32_swap_b32_e32 v33, v34
	v_add_f32_e32 v33, v33, v34
	v_mov_b32_e32 v34, v33
	s_nop 1
	v_permlane16_swap_b32_e32 v33, v34
	v_add_f32_e32 v33, v33, v34
	s_nop 1
	v_add_f32_dpp v33, v33, v33 row_ror:8 row_mask:0xf bank_mask:0xf
	s_nop 1
	v_add_f32_dpp v33, v33, v33 row_ror:4 row_mask:0xf bank_mask:0xf
	global_load_dwordx4 v[34:37], v[42:43], off
	global_load_dwordx4 v[54:57], v[42:43], off offset:1024
	global_load_dwordx4 v[58:61], v[44:45], off
	global_load_dwordx4 v[62:65], v[44:45], off offset:1024
	global_load_dwordx4 v[66:69], v[42:43], off offset:2048
	global_load_dwordx4 v[70:73], v[42:43], off offset:3072
	global_load_dwordx4 v[80:83], v[44:45], off offset:2048
	global_load_dwordx4 v[84:87], v[44:45], off offset:3072
	s_nop 1
	v_add_f32_dpp v33, v33, v33 row_ror:2 row_mask:0xf bank_mask:0xf
	s_nop 1
	v_add_f32_dpp v33, v33, v33 row_ror:1 row_mask:0xf bank_mask:0xf
	v_mul_f32_e32 v38, 0x3a800000, v33
	v_pk_add_f32 v[12:13], v[12:13], v[38:39] op_sel_hi:[1,0] neg_lo:[0,1] neg_hi:[0,1]
	v_pk_add_f32 v[14:15], v[14:15], v[38:39] op_sel_hi:[1,0] neg_lo:[0,1] neg_hi:[0,1]
	v_pk_add_f32 v[8:9], v[8:9], v[38:39] op_sel_hi:[1,0] neg_lo:[0,1] neg_hi:[0,1]
	v_pk_add_f32 v[10:11], v[10:11], v[38:39] op_sel_hi:[1,0] neg_lo:[0,1] neg_hi:[0,1]
	v_pk_add_f32 v[4:5], v[4:5], v[38:39] op_sel_hi:[1,0] neg_lo:[0,1] neg_hi:[0,1]
	v_pk_add_f32 v[6:7], v[6:7], v[38:39] op_sel_hi:[1,0] neg_lo:[0,1] neg_hi:[0,1]
	v_pk_add_f32 v[0:1], v[0:1], v[38:39] op_sel_hi:[1,0] neg_lo:[0,1] neg_hi:[0,1]
	v_pk_add_f32 v[2:3], v[2:3], v[38:39] op_sel_hi:[1,0] neg_lo:[0,1] neg_hi:[0,1]
	v_pk_mul_f32 v[38:39], v[12:13], v[12:13]
	v_pk_mul_f32 v[88:89], v[14:15], v[14:15]
	v_add_f32_e32 v33, v38, v39
	v_add_f32_e32 v33, v88, v33
	v_pk_mul_f32 v[90:91], v[8:9], v[8:9]
	v_add_f32_e32 v33, v89, v33
	v_add_f32_e32 v33, v90, v33
	v_pk_mul_f32 v[92:93], v[10:11], v[10:11]
	v_add_f32_e32 v33, v91, v33
	v_add_f32_e32 v33, v92, v33
	v_pk_mul_f32 v[94:95], v[4:5], v[4:5]
	v_add_f32_e32 v33, v93, v33
	v_add_f32_e32 v33, v94, v33
	v_pk_mul_f32 v[96:97], v[6:7], v[6:7]
	v_add_f32_e32 v33, v95, v33
	v_add_f32_e32 v33, v96, v33
	v_pk_mul_f32 v[98:99], v[0:1], v[0:1]
	v_add_f32_e32 v33, v97, v33
	v_add_f32_e32 v33, v98, v33
	v_pk_mul_f32 v[100:101], v[2:3], v[2:3]
	v_add_f32_e32 v33, v99, v33
	v_add_f32_e32 v33, v100, v33
	v_add_f32_e32 v33, v101, v33
	v_mov_b32_e32 v38, v33
	s_nop 1
	v_permlane32_swap_b32_e32 v33, v38
	v_add_f32_e32 v33, v33, v38
	v_mov_b32_e32 v38, v33
	s_nop 1
	v_permlane16_swap_b32_e32 v33, v38
	v_add_f32_e32 v33, v33, v38
	s_nop 1
	v_add_f32_dpp v33, v33, v33 row_ror:8 row_mask:0xf bank_mask:0xf
	s_nop 1
	v_add_f32_dpp v33, v33, v33 row_ror:4 row_mask:0xf bank_mask:0xf
	s_nop 1
	v_add_f32_dpp v33, v33, v33 row_ror:2 row_mask:0xf bank_mask:0xf
	s_nop 1
	v_add_f32_dpp v33, v33, v33 row_ror:1 row_mask:0xf bank_mask:0xf
	v_fmamk_f32 v33, v33, 0x3a800000, v175
	v_mul_f32_e32 v38, 0x4b800000, v33
	v_cmp_gt_f32_e32 vcc, s66, v33
	s_nop 1
	v_cndmask_b32_e32 v33, v33, v38, vcc
	v_rsq_f32_e32 v33, v33
	s_nop 0
	v_mul_f32_e32 v38, 0x45800000, v33
	v_cndmask_b32_e32 v38, v33, v38, vcc
	v_pk_mul_f32 v[12:13], v[12:13], v[38:39] op_sel_hi:[1,0]
	v_pk_mul_f32 v[14:15], v[14:15], v[38:39] op_sel_hi:[1,0]
	v_pk_mul_f32 v[8:9], v[8:9], v[38:39] op_sel_hi:[1,0]
	v_pk_mul_f32 v[10:11], v[10:11], v[38:39] op_sel_hi:[1,0]
	v_pk_mul_f32 v[4:5], v[4:5], v[38:39] op_sel_hi:[1,0]
	v_pk_mul_f32 v[6:7], v[6:7], v[38:39] op_sel_hi:[1,0]
	v_pk_mul_f32 v[0:1], v[0:1], v[38:39] op_sel_hi:[1,0]
	v_pk_mul_f32 v[2:3], v[2:3], v[38:39] op_sel_hi:[1,0]
	s_waitcnt vmcnt(5)
	v_pk_fma_f32 v[12:13], v[34:35], v[12:13], v[58:59]
	v_pk_fma_f32 v[14:15], v[36:37], v[14:15], v[60:61]
	s_waitcnt vmcnt(4)
	v_pk_fma_f32 v[8:9], v[54:55], v[8:9], v[62:63]
	v_pk_fma_f32 v[10:11], v[56:57], v[10:11], v[64:65]
	s_waitcnt vmcnt(1)
	v_pk_fma_f32 v[4:5], v[66:67], v[4:5], v[80:81]
	v_pk_fma_f32 v[6:7], v[68:69], v[6:7], v[82:83]
	s_waitcnt vmcnt(0)
	v_pk_fma_f32 v[0:1], v[70:71], v[0:1], v[84:85]
	v_pk_fma_f32 v[2:3], v[72:73], v[2:3], v[86:87]
; DEV unsigned cvtpk(float lo, float hi) { unsigned r; asm("v_cvt_pk_bf16_f32 %0, %1, %2" : "=v"(r) : "v"(lo), "v"(hi)); return r; }
; DEV void phase_ln(const Params& p, int l) {
;     ...
;     { float* dst = X + (size_t)R * 1024;
; #pragma unroll
;       for (int q = 0; q < 4; ++q) *reinterpret_cast<float4*>(dst + q * 256 + lane * 4) = make_float4(v[q * 4], v[q * 4 + 1], v[q * 4 + 2], v[q * 4 + 3]); }
;     float s = 0;
; #pragma unroll
;     for (int i = 0; i < 16; ++i) s += v[i];
;     float mean = wave_sum(s, lane) * (1.f / 1024.f);
;     float q2 = 0;
; #pragma unroll
;     for (int i = 0; i < 16; ++i) { v[i] -= mean; q2 += v[i] * v[i]; }
;     float rstd = rsqrtf(wave_sum(q2, lane) * (1.f / 1024.f) + LN_EPS);
;     const float* md = MOD + (size_t)(l * 5 + bidx) * 3072;
; #pragma unroll
;     for (int q = 0; q < 4; ++q) {
;       float4 sh = *reinterpret_cast<const float4*>(md + q * 256 + lane * 4); float4 sc = *reinterpret_cast<const float4*>(md + 1024 + q * 256 + lane * 4);
;       float h0 = v[q * 4] * rstd * (1.f + sc.x) + sh.x, h1 = v[q * 4 + 1] * rstd * (1.f + sc.y) + sh.y;
;       float h2 = v[q * 4 + 2] * rstd * (1.f + sc.z) + sh.z, h3 = v[q * 4 + 3] * rstd * (1.f + sc.w) + sh.w;
;       u32x2 o = {cvtpk(h0, h1), cvtpk(h2, h3)};
;       *reinterpret_cast<u32x2*>(H + (size_t)R * 1024 + q * 256 + lane * 4) = o;
;     }
.LBB0_167:
	s_mov_b64 s[0:1], -1
	s_and_b64 vcc, exec, s[2:3]
	s_cbranch_vccz .LBB0_169
	v_min_i32_e32 v32, 0x4000, v32
	v_ashrrev_i32_e32 v79, 12, v32
	v_lshl_add_u64 v[32:33], v[46:47], 0, s[14:15]
	v_add_co_u32_e32 v32, vcc, 0x9800000, v32
	v_lshlrev_b32_e32 v162, 2, v40
	s_nop 0
	v_addc_co_u32_e32 v33, vcc, 0, v33, vcc
	global_store_dwordx4 v[32:33], v[12:15], off
	global_store_dwordx4 v[32:33], v[8:11], off offset:1024
	global_store_dwordx4 v[32:33], v[4:7], off offset:2048
	global_store_dwordx4 v[32:33], v[0:3], off offset:3072
	v_add_f32_e32 v32, 0, v12
	v_add_f32_e32 v32, v13, v32
	v_add_f32_e32 v32, v14, v32
	v_add_f32_e32 v32, v15, v32
	v_add_f32_e32 v32, v8, v32
	v_add_f32_e32 v32, v9, v32
	v_add_f32_e32 v32, v10, v32
	v_add_f32_e32 v32, v11, v32
	v_add_f32_e32 v32, v4, v32
	v_add_f32_e32 v32, v5, v32
	v_add_f32_e32 v32, v6, v32
	v_add_f32_e32 v32, v7, v32
	v_add_f32_e32 v32, v0, v32
	v_add_f32_e32 v32, v1, v32
	v_add_f32_e32 v32, v2, v32
	v_add_f32_e32 v32, v3, v32
	v_mov_b32_e32 v33, v32
	s_nop 1
	v_permlane32_swap_b32_e32 v32, v33
	v_add_f32_e32 v32, v32, v33
	v_mov_b32_e32 v33, v32
	s_nop 1
	v_permlane16_swap_b32_e32 v32, v33
	v_add_f32_e32 v32, v32, v33
	s_nop 1
	v_add_f32_dpp v32, v32, v32 row_ror:8 row_mask:0xf bank_mask:0xf
	s_nop 1
	v_add_f32_dpp v32, v32, v32 row_ror:4 row_mask:0xf bank_mask:0xf
	s_nop 1
	v_add_f32_dpp v32, v32, v32 row_ror:2 row_mask:0xf bank_mask:0xf
	s_nop 1
	v_add_f32_dpp v32, v32, v32 row_ror:1 row_mask:0xf bank_mask:0xf
	v_mul_f32_e32 v32, 0x3a800000, v32
	v_pk_add_f32 v[68:69], v[12:13], v[32:33] op_sel_hi:[1,0] neg_lo:[0,1] neg_hi:[0,1]
	v_pk_add_f32 v[66:67], v[14:15], v[32:33] op_sel_hi:[1,0] neg_lo:[0,1] neg_hi:[0,1]
	v_pk_mul_f32 v[34:35], v[68:69], v[68:69]
	v_pk_mul_f32 v[36:37], v[66:67], v[66:67]
	v_add_f32_e32 v34, v34, v35
	v_pk_add_f32 v[64:65], v[8:9], v[32:33] op_sel_hi:[1,0] neg_lo:[0,1] neg_hi:[0,1]
	v_add_f32_e32 v34, v36, v34
	v_pk_mul_f32 v[38:39], v[64:65], v[64:65]
	v_add_f32_e32 v34, v37, v34
	v_pk_add_f32 v[62:63], v[10:11], v[32:33] op_sel_hi:[1,0] neg_lo:[0,1] neg_hi:[0,1]
	v_add_f32_e32 v34, v38, v34
	v_pk_mul_f32 v[70:71], v[62:63], v[62:63]
	v_add_f32_e32 v34, v39, v34
	v_pk_add_f32 v[60:61], v[4:5], v[32:33] op_sel_hi:[1,0] neg_lo:[0,1] neg_hi:[0,1]
	v_add_f32_e32 v34, v70, v34
	v_pk_mul_f32 v[72:73], v[60:61], v[60:61]
	v_add_f32_e32 v34, v71, v34
	v_pk_add_f32 v[58:59], v[6:7], v[32:33] op_sel_hi:[1,0] neg_lo:[0,1] neg_hi:[0,1]
	v_add_f32_e32 v34, v72, v34
	v_pk_mul_f32 v[80:81], v[58:59], v[58:59]
	v_add_f32_e32 v34, v73, v34
	v_pk_add_f32 v[56:57], v[0:1], v[32:33] op_sel_hi:[1,0] neg_lo:[0,1] neg_hi:[0,1]
	v_add_f32_e32 v34, v80, v34
	v_pk_mul_f32 v[82:83], v[56:57], v[56:57]
	v_add_f32_e32 v34, v81, v34
	v_pk_add_f32 v[54:55], v[2:3], v[32:33] op_sel_hi:[1,0] neg_lo:[0,1] neg_hi:[0,1]
	v_add_f32_e32 v34, v82, v34
	v_pk_mul_f32 v[32:33], v[54:55], v[54:55]
	v_add_f32_e32 v34, v83, v34
	v_add_f32_e32 v32, v32, v34
	v_add_f32_e32 v32, v33, v32
	v_mov_b32_e32 v33, v32
	v_add_u32_e32 v34, s21, v79
	s_nop 1
	v_permlane32_swap_b32_e32 v32, v33
	v_add_f32_e32 v32, v32, v33
	v_mov_b32_e32 v33, v32
	s_nop 1
	v_permlane16_swap_b32_e32 v32, v33
	v_add_f32_e32 v32, v32, v33
	s_nop 1
	v_add_f32_dpp v32, v32, v32 row_ror:8 row_mask:0xf bank_mask:0xf
	s_nop 1
	v_add_f32_dpp v32, v32, v32 row_ror:4 row_mask:0xf bank_mask:0xf
	s_nop 1
	v_add_f32_dpp v32, v32, v32 row_ror:2 row_mask:0xf bank_mask:0xf
	s_nop 1
	v_add_f32_dpp v32, v32, v32 row_ror:1 row_mask:0xf bank_mask:0xf
	v_fmamk_f32 v32, v32, 0x3a800000, v175
	v_cmp_gt_f32_e32 vcc, s66, v32
	v_mul_f32_e32 v33, 0x4b800000, v32
	s_nop 0
	v_cndmask_b32_e32 v32, v32, v33, vcc
	v_rsq_f32_e32 v32, v32
	s_nop 0
	v_mul_f32_e32 v33, 0x45800000, v32
	v_cndmask_b32_e32 v53, v32, v33, vcc
	v_mov_b64_e32 v[32:33], s[10:11]
	v_mad_i64_i32 v[32:33], s[0:1], v34, s80, v[32:33]
	v_lshl_add_u64 v[72:73], v[32:33], 0, v[162:163]
	v_add_co_u32_e32 v36, vcc, s87, v72
	global_load_dwordx4 v[32:35], v[72:73], off
	s_nop 0
	v_addc_co_u32_e32 v37, vcc, 0, v73, vcc
	global_load_dwordx4 v[36:39], v[36:37], off
	v_mul_f32_e32 v68, v68, v53
	v_lshl_add_u64 v[70:71], v[72:73], 0, s[84:85]
	v_mul_f32_e32 v64, v64, v53
	v_mul_f32_e32 v60, v60, v53
	v_mul_f32_e32 v56, v56, v53
	s_mov_b64 s[0:1], 0
	s_waitcnt vmcnt(0)
	v_add_f32_e32 v36, 1.0, v36
	v_fma_f32 v32, v36, v68, v32
	v_mul_f32_e32 v36, v69, v53
	v_add_f32_e32 v37, 1.0, v37
	v_fma_f32 v33, v37, v36, v33
	v_mul_f32_e32 v36, v66, v53
	v_add_f32_e32 v37, 1.0, v38
	v_fma_f32 v34, v37, v36, v34
	v_mul_f32_e32 v36, v67, v53
	v_add_f32_e32 v37, 1.0, v39
	v_fmac_f32_e32 v35, v37, v36
	v_cvt_pk_bf16_f32 v32, v32, v33
	v_cvt_pk_bf16_f32 v33, v34, v35
	global_store_dwordx2 v[50:51], v[32:33], off offset:-1024
	global_load_dwordx4 v[32:35], v[72:73], off offset:1024
	s_nop 0
	global_load_dwordx4 v[36:39], v[70:71], off offset:1024
	s_waitcnt vmcnt(0)
	v_add_f32_e32 v36, 1.0, v36
	v_fma_f32 v32, v36, v64, v32
	v_mul_f32_e32 v36, v65, v53
	v_add_f32_e32 v37, 1.0, v37
	v_fma_f32 v33, v37, v36, v33
	v_mul_f32_e32 v36, v62, v53
	v_add_f32_e32 v37, 1.0, v38
	v_fma_f32 v34, v37, v36, v34
	v_mul_f32_e32 v36, v63, v53
	v_add_f32_e32 v37, 1.0, v39
	v_fmac_f32_e32 v35, v37, v36
	v_cvt_pk_bf16_f32 v32, v32, v33
	v_cvt_pk_bf16_f32 v33, v34, v35
	global_store_dwordx2 v[50:51], v[32:33], off offset:-512
	global_load_dwordx4 v[32:35], v[72:73], off offset:2048
	s_nop 0
	global_load_dwordx4 v[36:39], v[70:71], off offset:2048
	s_waitcnt vmcnt(0)
	v_add_f32_e32 v36, 1.0, v36
	v_fma_f32 v32, v60, v36, v32
	v_mul_f32_e32 v36, v61, v53
	v_add_f32_e32 v37, 1.0, v37
	v_fma_f32 v33, v36, v37, v33
	v_mul_f32_e32 v36, v58, v53
	v_add_f32_e32 v37, 1.0, v38
	v_fma_f32 v34, v36, v37, v34
	v_mul_f32_e32 v36, v59, v53
	v_add_f32_e32 v37, 1.0, v39
	v_fmac_f32_e32 v35, v36, v37
	v_cvt_pk_bf16_f32 v32, v32, v33
	v_cvt_pk_bf16_f32 v33, v34, v35
	global_store_dwordx2 v[50:51], v[32:33], off
	global_load_dwordx4 v[32:35], v[72:73], off offset:3072
	s_nop 0
	global_load_dwordx4 v[36:39], v[70:71], off offset:3072
	s_waitcnt vmcnt(0)
	v_add_f32_e32 v36, 1.0, v36
	v_fma_f32 v32, v56, v36, v32
	v_mul_f32_e32 v36, v57, v53
	v_add_f32_e32 v37, 1.0, v37
	v_fma_f32 v33, v36, v37, v33
	v_mul_f32_e32 v36, v54, v53
	v_add_f32_e32 v37, 1.0, v38
	v_fma_f32 v34, v36, v37, v34
	v_mul_f32_e32 v36, v55, v53
	v_add_f32_e32 v37, 1.0, v39
	v_fmac_f32_e32 v35, v36, v37
	v_cvt_pk_bf16_f32 v32, v32, v33
	v_cvt_pk_bf16_f32 v33, v34, v35
	global_store_dwordx2 v[50:51], v[32:33], off offset:512
